# S5 loops: alternate s_setprio per iteration between the two waves sharing a SIMD (fair progress, removes 13us wave skew at S5 exit)
# speedup vs baseline: 1.0080x; 1.0034x over previous
.LBB0_644:
	v_readfirstlane_b32 s83, v144
	s_nop 3
	s_lshr_b32 s83, s83, 8
	s_waitcnt vmcnt(0)
	v_lshrrev_b32_e32 v0, 7, v144
	v_lshl_add_u32 v21, s3, 2, v0
	v_and_b32_e32 v70, 63, v144
	v_bfe_u32 v67, v144, 6, 1
	v_and_b32_e32 v64, 63, v21
	v_lshl_or_b32 v20, v67, 6, v64
	v_lshlrev_b32_e32 v0, 2, v70
	v_lshl_or_b32 v0, v20, 8, v0
	v_lshlrev_b32_e32 v2, 2, v20
	s_waitcnt lgkmcnt(0)
	global_load_dword v1, v0, s[42:43]
	global_load_dword v11, v2, s[44:45]
	global_load_dword v22, v0, s[40:41]
	s_mov_b32 s8, 0x652b82fe
	s_mov_b32 s9, 0x3ff71547
	s_mov_b32 s6, 0xfefa39ef
	s_mov_b32 s7, 0xbfe62e42
	s_mov_b32 s0, 0x3b39803f
	s_mov_b32 s1, 0xbc7abc9e
	s_mov_b32 s10, 0x6a5dcb37
	v_mov_b32_e32 v2, 0xfca7ab0c
	v_mov_b32_e32 v3, 0x3e928af3
	s_mov_b32 s11, 0x3e5ade15
	v_mov_b32_e32 v4, 0x623fde64
	v_mov_b32_e32 v5, 0x3ec71dee
	v_mov_b32_e32 v6, 0x7c89e6b0
	v_mov_b32_e32 v7, 0x3efa0199
	v_mov_b32_e32 v8, 0x14761f6e
	v_mov_b32_e32 v9, 0x3f2a01a0
	v_mov_b32_e32 v12, 0x1852b7b0
	v_mov_b32_e32 v13, 0x3f56c16c
	v_mov_b32_e32 v14, 0x11122322
	v_mov_b32_e32 v15, 0x3f811111
	v_mov_b32_e32 v16, 0x555502a1
	v_mov_b32_e32 v17, 0x3fa55555
	v_mov_b32_e32 v18, 0x55555511
	v_mov_b32_e32 v19, 0x3fc55555
	v_mov_b32_e32 v24, 11
	v_mov_b32_e32 v25, 0x3fe00000
	s_mov_b32 s2, 0x44800000
	s_mov_b32 s14, 0xc4866000
	v_mov_b32_e32 v23, 0x7ff00000
	s_mov_b32 s12, 0
	s_mov_b32 s13, 0x41d00000
	v_mov_b32_e32 v10, 0
	s_waitcnt vmcnt(1)
	v_cvt_f64_f32_e32 v[26:27], v11
	v_mul_f64 v[28:29], v[26:27], s[8:9]
	v_rndne_f64_e32 v[28:29], v[28:29]
	v_fmac_f64_e32 v[26:27], s[6:7], v[28:29]
	v_fmac_f64_e32 v[26:27], s[0:1], v[28:29]
	v_fmac_f64_e32 v[2:3], s[10:11], v[26:27]
	v_fmac_f64_e32 v[4:5], v[26:27], v[2:3]
	v_fmac_f64_e32 v[6:7], v[26:27], v[4:5]
	v_fmac_f64_e32 v[8:9], v[26:27], v[6:7]
	v_fmac_f64_e32 v[12:13], v[26:27], v[8:9]
	v_fmac_f64_e32 v[14:15], v[26:27], v[12:13]
	v_fmac_f64_e32 v[16:17], v[26:27], v[14:15]
	v_fmac_f64_e32 v[18:19], v[26:27], v[16:17]
	v_fmac_f64_e32 v[24:25], v[26:27], v[18:19]
	v_fma_f64 v[2:3], v[26:27], v[24:25], 1.0
	v_cvt_i32_f64_e32 v30, v[28:29]
	v_fma_f64 v[2:3], v[26:27], v[2:3], 1.0
	v_ldexp_f64 v[2:3], v[2:3], v30
	v_cmp_nlt_f32_e32 vcc, s2, v11
	v_cmp_ngt_f32_e64 s[0:1], s14, v11
	v_cvt_f64_f32_e32 v[0:1], v1
	v_cndmask_b32_e32 v3, v23, v3, vcc
	s_and_b64 vcc, s[0:1], vcc
	v_cndmask_b32_e64 v9, 0, v3, s[0:1]
	v_cndmask_b32_e32 v8, 0, v2, vcc
	v_mul_f64 v[2:3], v[8:9], v[0:1]
	v_cmp_nlt_f64_e64 s[6:7], |v[2:3]|, s[12:13]
	v_trig_preop_f64 v[18:19], |v[2:3]|, 0
	v_trig_preop_f64 v[16:17], |v[2:3]|, 1
	v_trig_preop_f64 v[12:13], |v[2:3]|, 2
	s_and_saveexec_b64 s[0:1], s[6:7]
	s_xor_b64 s[8:9], exec, s[0:1]
	s_cbranch_execz .LBB0_646
	s_mov_b32 s0, 0
	s_mov_b32 s1, 0x7b000000
	s_movk_i32 s2, 0xff80
	v_and_b32_e32 v6, 0x7fffffff, v3
	v_ldexp_f64 v[4:5], |v[2:3]|, s2
	v_cmp_ge_f64_e64 vcc, |v[2:3]|, s[0:1]
	s_mov_b32 s0, 0
	s_mov_b32 s1, 0x7ff00000
	v_cndmask_b32_e32 v5, v6, v5, vcc
	v_cndmask_b32_e32 v4, v2, v4, vcc
	v_mul_f64 v[14:15], v[18:19], v[4:5]
	v_mul_f64 v[6:7], v[16:17], v[4:5]
	v_fma_f64 v[24:25], v[18:19], v[4:5], -v[14:15]
	v_add_f64 v[26:27], v[6:7], v[24:25]
	v_add_f64 v[34:35], v[26:27], -v[6:7]
	v_add_f64 v[24:25], v[24:25], -v[34:35]
	v_add_f64 v[34:35], v[26:27], -v[34:35]
	v_add_f64 v[34:35], v[6:7], -v[34:35]
	v_add_f64 v[24:25], v[24:25], v[34:35]
	v_fma_f64 v[6:7], v[16:17], v[4:5], -v[6:7]
	v_mul_f64 v[34:35], v[12:13], v[4:5]
	v_add_f64 v[36:37], v[34:35], v[6:7]
	v_add_f64 v[28:29], v[14:15], v[26:27]
	v_add_f64 v[38:39], v[36:37], v[24:25]
	v_ldexp_f64 v[30:31], v[28:29], -2
	v_add_f64 v[14:15], v[28:29], -v[14:15]
	v_add_f64 v[28:29], v[38:39], -v[36:37]
	v_add_f64 v[24:25], v[24:25], -v[28:29]
	v_add_f64 v[28:29], v[38:39], -v[28:29]
	v_add_f64 v[28:29], v[36:37], -v[28:29]
	v_add_f64 v[24:25], v[24:25], v[28:29]
	v_add_f64 v[28:29], v[36:37], -v[34:35]
	v_add_f64 v[6:7], v[6:7], -v[28:29]
	v_add_f64 v[28:29], v[36:37], -v[28:29]
	v_add_f64 v[28:29], v[34:35], -v[28:29]
	v_add_f64 v[14:15], v[26:27], -v[14:15]
	v_add_f64 v[6:7], v[6:7], v[28:29]
	v_fract_f64_e32 v[32:33], v[30:31]
	v_add_f64 v[26:27], v[14:15], v[38:39]
	v_add_f64 v[6:7], v[6:7], v[24:25]
	v_fma_f64 v[4:5], v[12:13], v[4:5], -v[34:35]
	v_add_f64 v[14:15], v[26:27], -v[14:15]
	v_add_f64 v[4:5], v[4:5], v[6:7]
	v_ldexp_f64 v[6:7], v[32:33], 2
	v_cmp_neq_f64_e64 vcc, |v[30:31]|, s[0:1]
	v_add_f64 v[14:15], v[38:39], -v[14:15]
	v_add_f64 v[4:5], v[14:15], v[4:5]
	v_cndmask_b32_e32 v7, 0, v7, vcc
	v_cndmask_b32_e32 v6, 0, v6, vcc
	v_add_f64 v[14:15], v[26:27], v[6:7]
	v_mov_b32_e32 v11, 0x40100000
	v_cmp_gt_f64_e32 vcc, 0, v[14:15]
	s_mov_b32 s10, 0x33145c07
	s_mov_b32 s11, 0x3c91a626
	v_cndmask_b32_e32 v11, 0, v11, vcc
	v_add_f64 v[6:7], v[6:7], v[10:11]
	v_add_f64 v[14:15], v[26:27], v[6:7]
	v_cvt_i32_f64_e32 v11, v[14:15]
	v_cvt_f64_i32_e32 v[14:15], v11
	v_add_f64 v[6:7], v[6:7], -v[14:15]
	v_add_f64 v[14:15], v[26:27], v[6:7]
	v_add_f64 v[6:7], v[14:15], -v[6:7]
	v_add_f64 v[6:7], v[26:27], -v[6:7]
	v_add_f64 v[4:5], v[4:5], v[6:7]
	v_cmp_le_f64_e32 vcc, 0.5, v[14:15]
	v_mov_b32_e32 v6, 0x3ff00000
	s_nop 0
	v_addc_co_u32_e64 v23, s[0:1], 0, v11, vcc
	v_cndmask_b32_e32 v11, 0, v6, vcc
	v_add_f64 v[6:7], v[14:15], -v[10:11]
	v_add_f64 v[10:11], v[6:7], v[4:5]
	s_mov_b32 s0, 0x54442d18
	v_add_f64 v[6:7], v[10:11], -v[6:7]
	s_mov_b32 s1, 0x3ff921fb
	v_add_f64 v[4:5], v[4:5], -v[6:7]
	v_mul_f64 v[6:7], v[10:11], s[0:1]
	v_fma_f64 v[14:15], v[10:11], s[0:1], -v[6:7]
	v_fmac_f64_e32 v[14:15], s[10:11], v[10:11]
	v_fmac_f64_e32 v[14:15], s[0:1], v[4:5]
	v_add_f64 v[4:5], v[6:7], v[14:15]
	v_add_f64 v[6:7], v[4:5], -v[6:7]
	v_add_f64 v[6:7], v[14:15], -v[6:7]
	s_andn2_saveexec_b64 s[0:1], s[8:9]
	s_cbranch_execz .LBB0_648
	s_branch .LBB0_647

.LBB0_653:
	s_xor_b32 s83, s83, 1
	s_cmp_eq_u32 s83, 0
	s_cbranch_scc1 .Lfp0_0
	s_setprio 1
	s_branch .Lfpe_0
.Lfp0_0:
	s_setprio 0

.LBB0_759:
	s_setprio 0
	s_mov_b32 s14, s3
	s_mov_b32 s54, 1
	s_barrier
